# mixer phase: workgroups with blockIdx bit 3 set run A pass 1 + D before B + SSD part 1 (others keep the order), so only half of the CUs hammer L2 with K/V tiles at any time
# speedup vs baseline: 1.0303x; 1.0303x over previous
; #define LAS __attribute__((address_space(3)))
; __global__ void __launch_bounds__(512) fwd_kernel(Args a) {
;     extern __shared__ __attribute__((aligned(16))) unsigned char lds_raw[];
;     cg::grid_group grid = cg::this_grid();
;     LAS unsigned char* lds = (LAS unsigned char*)lds_raw;
;     const int wave0 = __builtin_amdgcn_readfirstlane(threadIdx.x >> 6), G = gridDim.x;
;     ...
;     const int lo = a.ph_lo, hi = a.ph_hi;
;     if (hi > 1000) grid.sync();
_Z10fwd_kernel4Args:
	s_mov_b32 s100, 0
	s_mov_b32 s101, 0
	s_load_dwordx8 s[76:83], s[0:1], 0x80
	s_load_dword s3, s[0:1], 0xa8
	s_load_dwordx2 s[88:89], s[0:1], 0xa0
	s_add_u32 s6, s0, 0xa0
	s_addc_u32 s7, s1, 0
	v_and_b32_e32 v1, 0x3ff, v0
	s_mov_b32 s66, s2
	s_movk_i32 s4, 0x3ff
	s_waitcnt lgkmcnt(0)
	s_cmpk_lt_i32 s83, 0x3e9
	v_readfirstlane_b32 s2, v1
	s_cbranch_scc1 .LBB0_12
	v_lshrrev_b32_e32 v2, 20, v0
	v_lshrrev_b32_e32 v0, 10, v0
	v_or_b32_e32 v0, v0, v2
	v_and_or_b32 v0, v0, s4, v1
	v_cmp_eq_u32_e32 vcc, 0, v0
	s_barrier
	s_and_saveexec_b64 s[4:5], vcc
	s_cbranch_execz .LBB0_11
	buffer_wbl2 sc1
	s_load_dwordx2 s[6:7], s[6:7], 0x58
	s_mov_b64 s[8:9], exec
	v_mbcnt_lo_u32_b32 v0, s8, 0
	v_mbcnt_hi_u32_b32 v0, s9, v0
	v_cmp_eq_u32_e32 vcc, 0, v0
	s_waitcnt lgkmcnt(0)
	s_load_dword s12, s[6:7], 0x28
	s_and_saveexec_b64 s[10:11], vcc
	s_cbranch_execz .LBB0_4
	s_bcnt1_i32_b64 s8, s[8:9]
	v_mov_b32_e32 v2, 0
	v_mov_b32_e32 v3, s8
	global_atomic_add v2, v2, v3, s[6:7] offset:32 sc0

; DI void mixerB2_unit(int u, int l, const bf16* PROJ, bf16* YC, const float* dlam_l, const float* dnw_l, const float* kmax_l, LAS char* lds, int tid, int wave, int lane) {
;     const int b = u >> 5, h = (u >> 3) & 3, qb = u & 7, r = lane & 15, g = lane >> 4, q = (lane & 15) >> 2, p = lane & 3;
;     const bf16* kbase = slab(PROJ, C_BK + h * 64, b); const bf16* vbase = slab(PROJ, C_BV + h * 64, b);
;     const bf16* qbase = slab(PROJ, C_BQ + h * 64, b); const bf16* gbase = slab(PROJ, C_BG + h * 64, b);
;     const int q0w = qb * 256 + wave * 32;
;     LAS char* Kb = lds; LAS char* Vb = lds + 2 * KV_TILE;
;     const float slope2 = ex2(-(float)(2 * h + 2)) * LOG2E;
;     __syncthreads();
;     bf16x8 q1[2], q2[2]; float bound[2];
;     LAS char* qs = lds + 92160 + wave * (32 * KV_PITCH);
; #pragma unroll
;     for (int qt = 0; qt < 2; ++qt) { const bf16* qp = qbase + (size_t)(q0w + 16 * qt + r) * 64 + 8 * g;
;         q1[qt] = *(const bf16x8*)qp; q2[qt] = *(const bf16x8*)(qp + 32);
;         *(LAS bf16x8*)(qs + (16 * qt + r) * KV_PITCH + 16 * g) = q1[qt]; *(LAS bf16x8*)(qs + (16 * qt + r) * KV_PITCH + 64 + 16 * g) = q2[qt]; }
;     const int lrow = tid >> 3, lch = tid & 7;
;     u32x4 rk = *(const u32x4*)(kbase + (size_t)lrow * 64 + lch * 8), rv = *(const u32x4*)(vbase + (size_t)lrow * 64 + lch * 8);
;     u32x4 rk2 = *(const u32x4*)(kbase + (size_t)(lrow + 64) * 64 + lch * 8), rv2 = *(const u32x4*)(vbase + (size_t)(lrow + 64) * 64 + lch * 8);
;     *(LAS u32x4*)(Kb + lrow * KV_PITCH + lch * 16) = rk; *(LAS u32x4*)(Vb + lrow * KV_PITCH + lch * 16) = rv;
;     *(LAS u32x4*)(Kb + (lrow + 64) * KV_PITCH + lch * 16) = rk2; *(LAS u32x4*)(Vb + (lrow + 64) * KV_PITCH + lch * 16) = rv2;
;     __syncthreads();
;     { const float k1 = kmax_l[b * 128 + 40 + 2 * h], k2 = kmax_l[b * 128 + 41 + 2 * h];
; #pragma unroll
;       for (int qt = 0; qt < 2; ++qt) { float a = sumsq8(q1[qt]), c = sumsq8(q2[qt]);
;           a += __shfl_xor(a, 16); a += __shfl_xor(a, 32); c += __shfl_xor(c, 16); c += __shfl_xor(c, 32);
; __global__ void __launch_bounds__(512) fwd_kernel(Args a) {
;     ...
;             if (EN_B) { LAUNDER(); LAS char* vt = (LAS char*)lds + wave * 16384;
;                 (void)vt; for (int u = blockIdx.x; u < 256; u += G) { mixerB2_unit(u, l, PROJ, YC, a.in[6] + l * 128, a.in[7] + l * 64, KMAX + l * 1024, (LAS char*)lds, tid, wave, lane); } __syncthreads(); }
.Lmx_b:
	s_cmp_eq_u32 s101, 0
	s_cbranch_scc0 .Lmx_b_go
	s_bitcmp1_b32 s66, 3
	s_cbranch_scc0 .Lmx_b_go
	s_mov_b32 s101, 1
	v_readlane_b32 s56, v255, 10
	s_branch .LBB0_356
.Lmx_b_go:
	v_readlane_b32 s0, v253, 0
	v_mbcnt_lo_u32_b32 v4, -1, 0
	v_mbcnt_hi_u32_b32 v4, -1, v4
	v_readlane_b32 s56, v255, 8
	s_waitcnt lgkmcnt(0)
	v_add_u32_e32 v5, s0, v4
	v_readlane_b32 s0, v253, 56
	v_readlane_b32 s1, v253, 57
	s_andn2_b64 vcc, exec, s[0:1]
	s_nop 0
	v_cndmask_b32_e64 v6, 0, 1, s[0:1]
	v_cmp_ne_u32_e64 s[36:37], 1, v6
	v_readfirstlane_b32 s0, v5
	s_cbranch_vccnz .LBB0_262
	v_readlane_b32 s60, v255, 27
	s_lshl_b32 s34, s60, 7
	v_readlane_b32 s40, v253, 26
	s_ashr_i32 s16, s0, 6
	s_lshl_b64 s[0:1], s[34:35], 2
	v_readlane_b32 s52, v253, 38
	v_readlane_b32 s53, v253, 39
	s_add_u32 s20, s52, s0
	s_addc_u32 s21, s53, s1
	s_lshl_b32 s34, s60, 6
	v_readlane_b32 s54, v253, 40
	s_lshl_b64 s[0:1], s[34:35], 2
	v_readlane_b32 s55, v253, 41
	s_add_u32 s0, s54, s0
	s_addc_u32 s1, s55, s1
	s_lshl_b32 s34, s60, 10
	s_lshl_b64 s[4:5], s[34:35], 2
	v_readlane_b32 s26, v253, 42
	v_readlane_b32 s27, v253, 43
	s_add_u32 s2, s26, s4
	s_mul_i32 s26, s16, 0x1200
	s_addc_u32 s4, s27, s5
	s_add_i32 s26, s26, 0
	s_add_i32 s26, s26, 0x16800
	v_and_b32_e32 v165, 15, v4
	v_mov_b32_e32 v6, s26
	s_movk_i32 s30, 0x90
	v_mad_u32_u24 v13, v165, s30, v6
	v_ashrrev_i32_e32 v6, 3, v5
	v_and_b32_e32 v5, 7, v4
	v_mul_lo_u32 v14, v6, s30
	v_lshlrev_b32_e32 v15, 4, v5
	v_add3_u32 v182, 0, v14, v15
	v_and_b32_e32 v14, 64, v224
	v_lshlrev_b32_e32 v170, 3, v5
	v_xor_b32_e32 v5, 16, v224
	v_add_u32_e32 v14, 64, v14
	v_cmp_lt_i32_e32 vcc, v5, v14
	v_bfe_u32 v11, v4, 4, 2
	v_bfe_u32 v12, v4, 2, 2
	v_cndmask_b32_e32 v5, v224, v5, vcc
	v_lshlrev_b32_e32 v184, 2, v5
	v_xor_b32_e32 v5, 32, v224
	v_cmp_lt_i32_e32 vcc, v5, v14
	v_lshlrev_b32_e32 v164, 3, v11
	v_and_b32_e32 v10, 63, v4
	v_cndmask_b32_e32 v5, v224, v5, vcc
	v_lshlrev_b32_e32 v185, 2, v5
	v_lshlrev_b32_e32 v5, 2, v11
	v_sub_u32_e32 v11, v5, v165
	v_or_b32_e32 v5, v5, v12
	v_mul_u32_u24_e32 v198, 0x90, v5
	v_lshlrev_b32_e32 v5, 3, v4
	v_and_b32_e32 v199, 24, v5
	v_or_b32_e32 v5, 48, v10
	v_mul_u32_u24_e32 v200, 0x90, v5
	v_xor_b32_e32 v5, 1, v224
	v_cmp_lt_i32_e32 vcc, v5, v14
	v_cmp_gt_u32_e64 s[38:39], 32, v10
	v_lshlrev_b32_e32 v188, 2, v10
	v_cndmask_b32_e32 v5, v224, v5, vcc
	v_lshlrev_b32_e32 v201, 2, v5
	v_xor_b32_e32 v5, 2, v224
	v_cvt_f32_u32_e32 v10, s60
	v_cmp_lt_i32_e32 vcc, v5, v14
	s_lshl_b32 s5, s16, 5
	s_mulk_i32 s16, 0x900
	v_cndmask_b32_e32 v5, v224, v5, vcc
	v_lshlrev_b32_e32 v202, 2, v5
	v_xor_b32_e32 v5, 4, v224
	v_cmp_lt_i32_e32 vcc, v5, v14
	v_mul_f32_e32 v10, 0xbe99999a, v10
	v_mul_f32_e32 v10, 0x3fb8aa3b, v10
	v_cndmask_b32_e32 v5, v224, v5, vcc
	v_lshlrev_b32_e32 v203, 2, v5
	v_xor_b32_e32 v5, 8, v224
	v_exp_f32_e32 v10, v10
	v_add_u32_e32 v16, 1, v11
	v_cmp_lt_i32_e32 vcc, v5, v14
	s_add_i32 s16, s16, 0
	v_cvt_f32_i32_e32 v186, v11
	v_cvt_f32_i32_e32 v187, v16
	v_add_u32_e32 v16, 2, v11
	v_add_u32_e32 v11, 3, v11
	v_cndmask_b32_e32 v5, v224, v5, vcc
	s_add_i32 s16, s16, 0x12000
	v_and_b32_e32 v166, 48, v4
	v_ashrrev_i32_e32 v7, 31, v6
	v_cvt_f32_i32_e32 v191, v16
	v_cvt_f32_i32_e32 v193, v11
	v_lshlrev_b32_e32 v204, 2, v5
	v_mov_b32_e32 v5, 0x3f4ccccd
	v_bfe_u32 v207, v4, 3, 3
	v_mov_b32_e32 v4, s16
	v_mov_b32_e32 v167, v189
	v_lshlrev_b64 v[168:169], 6, v[6:7]
	s_mov_b64 s[26:27], 0x1000
	v_fmamk_f32 v205, v10, 0xbf19999a, v5
	v_mad_u32_u24 v12, v165, s30, v4
	v_lshl_add_u64 v[174:175], s[0:1], 0, v[166:167]
	v_lshlrev_b64 v[4:5], 7, v[6:7]
	v_readlane_b32 s0, v255, 5
	v_lshl_add_u64 v[8:9], v[168:169], 0, s[26:27]
	v_add_u32_e32 v10, s16, v15
	v_mul_u32_u24_e32 v11, 0x90, v207
	v_or_b32_e32 v14, 32, v164
	v_or_b32_e32 v16, 64, v164
	v_or_b32_e32 v17, 0x60, v164
	v_or_b32_e32 v4, v4, v15
	v_readlane_b32 s1, v255, 6
	v_mul_u32_u24_e32 v171, 0x90, v165
	v_add_u32_e32 v183, 0x2400, v182
	v_lshl_add_u64 v[172:173], s[20:21], 0, v[188:189]
	v_sub_f32_e32 v206, 1.0, v205
	v_or_b32_e32 v208, 8, v207
	v_lshl_add_u64 v[176:177], s[0:1], 0, v[4:5]
	s_sub_i32 s16, 0, s5
	v_add_u32_e32 v167, v10, v11
	v_add_u32_e32 v209, v12, v164
	v_add_u32_e32 v210, v12, v14
	v_add_u32_e32 v211, v12, v16
	v_add_u32_e32 v212, v12, v17
	v_add_u32_e32 v213, v13, v166
	v_lshlrev_b64 v[178:179], 1, v[8:9]
	v_readlane_b32 s30, v255, 7
	s_mov_b32 s31, s66
	v_readlane_b32 s61, v255, 28
	v_readlane_b32 s41, v253, 27
	v_readlane_b32 s42, v253, 28
	v_readlane_b32 s43, v253, 29
	v_readlane_b32 s44, v253, 30
	v_readlane_b32 s45, v253, 31
	v_readlane_b32 s46, v253, 32
	v_readlane_b32 s47, v253, 33
	v_readlane_b32 s48, v253, 34
	v_readlane_b32 s49, v253, 35
	v_readlane_b32 s50, v253, 36
	v_readlane_b32 s51, v253, 37
	s_branch .LBB0_252

; #define LAS __attribute__((address_space(3)))
; #define LAUNDER() int tp = TID0(); const int tid = tp, lane = tp & 63, wave = __builtin_amdgcn_readfirstlane(tp >> 6); (void)tid; (void)lane; (void)wave
; __global__ void __launch_bounds__(512) fwd_kernel(Args a) {
;     ...
;             if (EN_S1) { LAUNDER(); __syncthreads();
;                 for (int u = blockIdx.x; u < 256; u += G) ssd_part1_unit(u, PROJ, DT, H, WDT + l * 16384, a.in[11] + l * 8, a.in[8] + l * 5 * 768, a.in[9] + l * 768, a.in[10] + l * 8, STATES, TOT, lds, tid, wave, lane);
;                 __syncthreads(); }
;             if (EN_A) { LAUNDER(); LAS char* vt = (LAS char*)lds + wave * 16384;
;                 for (int u = blockIdx.x; u < 512; u += G) { mixerA1_unit(u, PROJ, YC, LPA, KMAX + l * 1024, vt, wave, lane); } }
.LBB0_356:
	s_cmp_eq_u32 s101, 2
	s_cbranch_scc0 .Lmx_a1_go
	s_mov_b32 s101, 0
	v_readlane_b32 s94, v255, 33
	v_readlane_b32 s96, v255, 19
	v_readlane_b32 s95, v255, 34
	v_readlane_b32 s97, v255, 20
	s_branch .LBB0_369

; #define LAS __attribute__((address_space(3)))
; #define LAUNDER() int tp = TID0(); const int tid = tp, lane = tp & 63, wave = __builtin_amdgcn_readfirstlane(tp >> 6); (void)tid; (void)lane; (void)wave
; #define SEAM(k) do { if (lo <= (k) && (k) + 1 < hi) { XcdBarrier b2_ = bar; asm volatile("" : "+s"(b2_.bar)); xcd_barrier(b2_); } } while (0)
; __global__ void __launch_bounds__(512) fwd_kernel(Args a) {
;     ...
;             if (EN_D) { LAUNDER(); LAS char* vt = (LAS char*)lds + wave * 16384;
;                 int hcur = -1; float rmax = 0.f;
;                 for (int u = blockIdx.x; u < 512; u += G) { const int hd = (u >> 4) & 3; if (hd != hcur) { rmax = d_stage_rpb(a.in[14] + l * 4 * 15 * 31, hd, vt, lane); hcur = hd; }
;                     mixerD2_unit(u, PROJ, YC, rmax, KMAX + l * 1024, vt, wave, lane); } }
;         }
;         SEAM(pb + 2);
.LBB0_369:
	s_cmp_eq_u32 s101, 1
	s_cbranch_scc0 .Lmx_done
	s_mov_b32 s101, 2
	s_branch .Lmx_b
